# stack5 + forgetting-attention steady loop: the 32 packed bias adds (v_pk_add_f32) split into scalar v_add_f32 pairs (same bytes, bit-identical)
# baseline (speedup 1.0000x reference)
.LBB0_251:
	v_add_u32_e32 v0, s18, v225
	ds_read_b64_tr_b16 v[192:193], v0 offset:24576
	ds_read_b64_tr_b16 v[194:195], v0 offset:25088
	v_add_f32_e32 v2, v80, v81
	v_add_f32_e32 v2, v82, v2
	v_add_f32_e32 v2, v83, v2
	v_add_f32_e32 v2, v84, v2
	v_add_f32_e32 v2, v85, v2
	v_cvt_pk_bf16_f32 v156, v80, v81
	v_cvt_pk_bf16_f32 v157, v82, v83
	s_waitcnt lgkmcnt(9)
	v_mfma_f32_32x32x16_bf16 v[96:111], v[188:191], v[140:143], v[48:63]
	ds_read_b64_tr_b16 v[188:189], v0 offset:28672
	ds_read_b64_tr_b16 v[190:191], v0 offset:29184
	v_add_f32_e32 v2, v86, v2
	v_add_f32_e32 v2, v87, v2
	v_add_f32_e32 v2, v88, v2
	v_add_f32_e32 v2, v89, v2
	v_cvt_pk_bf16_f32 v158, v84, v85
	v_cvt_pk_bf16_f32 v159, v86, v87
	s_waitcnt lgkmcnt(10)
	v_mfma_f32_32x32x16_bf16 v[112:127], v[184:187], v[140:143], v[48:63]
	ds_read_b64_tr_b16 v[10:11], v0 offset:25600
	ds_read_b64_tr_b16 v[12:13], v0 offset:26112
	v_add_f32_e32 v2, v90, v2
	v_add_f32_e32 v2, v91, v2
	v_add_f32_e32 v2, v92, v2
	v_add_f32_e32 v2, v93, v2
	v_cvt_pk_bf16_f32 v152, v88, v89
	v_cvt_pk_bf16_f32 v153, v90, v91
	s_waitcnt lgkmcnt(11)
	v_mfma_f32_32x32x16_bf16 v[96:111], v[180:183], v[136:139], v[96:111]
	ds_read_b64_tr_b16 v[180:181], v0 offset:29696
	ds_read_b64_tr_b16 v[182:183], v0 offset:30208
	v_add_f32_e32 v2, v94, v2
	v_add_f32_e32 v2, v95, v2
	v_add_f32_e32 v2, v64, v2
	v_add_f32_e32 v2, v65, v2
	v_cvt_pk_bf16_f32 v154, v92, v93
	v_cvt_pk_bf16_f32 v155, v94, v95
	s_waitcnt lgkmcnt(12)
	v_mfma_f32_32x32x16_bf16 v[112:127], v[176:179], v[136:139], v[112:127]
	ds_read_b64_tr_b16 v[176:177], v0 offset:26624
	ds_read_b64_tr_b16 v[178:179], v0 offset:27136
	v_add_f32_e32 v2, v66, v2
	v_add_f32_e32 v2, v67, v2
	v_add_f32_e32 v2, v68, v2
	v_add_f32_e32 v6, v69, v2
	v_cvt_pk_bf16_f32 v148, v64, v65
	v_cvt_pk_bf16_f32 v149, v66, v67
	s_waitcnt lgkmcnt(13)
	v_mfma_f32_32x32x16_bf16 v[96:111], v[172:175], v[132:135], v[96:111]
	ds_read_b64_tr_b16 v[2:3], v0 offset:30720
	ds_read_b64_tr_b16 v[4:5], v0 offset:31232
	v_add_f32_e32 v6, v70, v6
	v_add_f32_e32 v6, v71, v6
	v_add_f32_e32 v6, v72, v6
	v_add_f32_e32 v14, v73, v6
	v_cvt_pk_bf16_f32 v150, v68, v69
	v_cvt_pk_bf16_f32 v151, v70, v71
	s_waitcnt lgkmcnt(14)
	v_mfma_f32_32x32x16_bf16 v[112:127], v[168:171], v[132:135], v[112:127]
	ds_read_b64_tr_b16 v[6:7], v0 offset:27648
	ds_read_b64_tr_b16 v[8:9], v0 offset:28160
	v_add_f32_e32 v14, v74, v14
	v_add_f32_e32 v14, v75, v14
	v_add_f32_e32 v14, v76, v14
	v_add_f32_e32 v14, v77, v14
	v_cvt_pk_bf16_f32 v144, v72, v73
	v_cvt_pk_bf16_f32 v145, v74, v75
	s_waitcnt lgkmcnt(14)
	v_mfma_f32_32x32x16_bf16 v[96:111], v[164:167], v[128:131], v[96:111]
	ds_read_b64_tr_b16 v[164:165], v0 offset:31744
	ds_read_b64_tr_b16 v[166:167], v0 offset:32256
	v_add_f32_e32 v0, v78, v14
	v_add_f32_e32 v0, v79, v0
	v_add_f32_e32 v0, 0, v0
	v_cvt_pk_bf16_f32 v146, v76, v77
	v_cvt_pk_bf16_f32 v147, v78, v79
	v_mfma_f32_32x32x16_bf16 v[112:127], v[160:163], v[128:131], v[112:127]
	v_lshl_add_u64 v[14:15], v[202:203], 0, s[54:55]
	s_add_i32 s18, s69, s38
	s_mov_b32 s19, m0
	s_mov_b32 m0, s18
	s_nop 0
	global_load_lds_dwordx4 v[14:15], off
	s_mov_b32 m0, s19
	v_lshl_add_u64 v[14:15], v[200:201], 0, s[54:55]
	s_add_i32 s18, s7, s59
	s_mov_b32 s19, m0
	s_mov_b32 m0, s18
	s_nop 0
	global_load_lds_dwordx4 v[14:15], off
	s_mov_b32 m0, s19
	ds_read_b128 v[64:67], v204
	ds_read_b128 v[68:71], v204 offset:32
	ds_read_b128 v[72:75], v204 offset:128
	v_add_f32_e32 v0, v230, v0
	s_waitcnt lgkmcnt(2)
	v_add_f32_e32 v82, v98, v66
	v_add_f32_e32 v83, v99, v67
	s_waitcnt lgkmcnt(1)
	v_add_f32_e32 v84, v100, v68
	v_add_f32_e32 v85, v101, v69
	s_waitcnt lgkmcnt(0)
	v_add_f32_e32 v14, v112, v72
	v_add_f32_e32 v15, v113, v73
	v_add_f32_e32 v66, v114, v74
	v_add_f32_e32 v67, v115, v75
	ds_read_b128 v[72:75], v204 offset:160
	v_add_f32_e32 v86, v102, v70
	v_add_f32_e32 v87, v103, v71
	v_add_f32_e32 v64, v96, v64
	v_add_f32_e32 v65, v97, v65
	v_max3_f32 v81, v82, v83, v15
	v_max_f32_e32 v80, v64, v65
	s_waitcnt lgkmcnt(0)
	v_add_f32_e32 v68, v116, v72
	v_add_f32_e32 v69, v117, v73
	v_add_f32_e32 v70, v118, v74
	v_add_f32_e32 v71, v119, v75
	ds_read_b128 v[72:75], v204 offset:64
	ds_read_b128 v[76:79], v204 offset:192
	v_max3_f32 v80, v80, v14, v66
	v_max3_f32 v80, v80, v67, v84
	v_max3_f32 v81, v81, v86, v87
	s_waitcnt lgkmcnt(1)
	v_add_f32_e32 v88, v104, v72
	v_add_f32_e32 v89, v105, v73
	s_waitcnt lgkmcnt(0)
	v_add_f32_e32 v72, v120, v76
	v_add_f32_e32 v73, v121, v77
	v_add_f32_e32 v90, v106, v74
	v_add_f32_e32 v91, v107, v75
	v_add_f32_e32 v74, v122, v78
	v_add_f32_e32 v75, v123, v79
	ds_read_b128 v[76:79], v204 offset:96
	ds_read_b128 v[94:97], v204 offset:224
	v_max3_f32 v80, v80, v85, v68
	v_max3_f32 v81, v81, v70, v71
	v_max3_f32 v80, v80, v69, v88
	v_max3_f32 v81, v81, v90, v91
	s_waitcnt lgkmcnt(1)
	v_add_f32_e32 v92, v108, v76
	v_add_f32_e32 v93, v109, v77
	s_waitcnt lgkmcnt(0)
	v_add_f32_e32 v76, v124, v94
	v_add_f32_e32 v77, v125, v95
	v_add_f32_e32 v94, v110, v78
	v_add_f32_e32 v95, v111, v79
	v_max3_f32 v80, v80, v89, v72
	v_max3_f32 v81, v81, v74, v75
	v_add_f32_e32 v78, v126, v96
	v_add_f32_e32 v79, v127, v97
	v_max3_f32 v80, v80, v73, v92
	v_max3_f32 v81, v81, v94, v95
	v_max3_f32 v80, v80, v93, v76
	v_max3_f32 v81, v81, v78, v79
	v_max3_f32 v80, v80, v77, v81
	v_mov_b32_e32 v81, v80
	s_nop 1
	v_permlane32_swap_b32_e32 v80, v81
	v_max_f32_e32 v81, v81, v81
	v_max_f32_e32 v80, v80, v80
	v_max_f32_e32 v80, v80, v81
	v_cmp_lt_f32_e32 vcc, s96, v80
	s_cmp_lg_u64 vcc, 0
	s_cselect_b64 s[18:19], -1, 0
	s_cbranch_vccnz .LBB0_259

.LBB0_254:
	s_add_i32 s18, s7, 0x2000
	s_cmpk_lg_i32 s7, 0x4000
	s_cselect_b32 s60, s18, 0
	v_add_u32_e32 v14, s69, v225
	ds_read_b64_tr_b16 v[168:169], v14 offset:24576
	ds_read_b64_tr_b16 v[170:171], v14 offset:25088
	v_add_f32_e32 v2, v80, v81
	v_add_f32_e32 v2, v82, v2
	v_add_f32_e32 v2, v83, v2
	v_add_f32_e32 v2, v84, v2
	v_add_f32_e32 v2, v85, v2
	v_cvt_pk_bf16_f32 v156, v80, v81
	v_cvt_pk_bf16_f32 v157, v82, v83
	s_waitcnt lgkmcnt(9)
	v_mfma_f32_32x32x16_bf16 v[96:111], v[112:115], v[140:143], v[48:63]
	ds_read_b64_tr_b16 v[164:165], v14 offset:28672
	ds_read_b64_tr_b16 v[166:167], v14 offset:29184
	v_add_f32_e32 v2, v86, v2
	v_add_f32_e32 v2, v87, v2
	v_add_f32_e32 v2, v88, v2
	v_add_f32_e32 v2, v89, v2
	v_cvt_pk_bf16_f32 v158, v84, v85
	v_cvt_pk_bf16_f32 v159, v86, v87
	s_waitcnt lgkmcnt(10)
	v_mfma_f32_32x32x16_bf16 v[112:127], v[160:163], v[140:143], v[48:63]
	ds_read_b64_tr_b16 v[10:11], v14 offset:25600
	ds_read_b64_tr_b16 v[12:13], v14 offset:26112
	v_add_f32_e32 v2, v90, v2
	v_add_f32_e32 v2, v91, v2
	v_add_f32_e32 v2, v92, v2
	v_add_f32_e32 v2, v93, v2
	v_cvt_pk_bf16_f32 v152, v88, v89
	v_cvt_pk_bf16_f32 v153, v90, v91
	s_waitcnt lgkmcnt(11)
	v_mfma_f32_32x32x16_bf16 v[96:111], v[192:195], v[136:139], v[96:111]
	ds_read_b64_tr_b16 v[160:161], v14 offset:29696
	ds_read_b64_tr_b16 v[162:163], v14 offset:30208
	v_add_f32_e32 v2, v94, v2
	v_add_f32_e32 v2, v95, v2
	v_add_f32_e32 v2, v64, v2
	v_add_f32_e32 v2, v65, v2
	v_cvt_pk_bf16_f32 v154, v92, v93
	v_cvt_pk_bf16_f32 v155, v94, v95
	s_waitcnt lgkmcnt(12)
	v_mfma_f32_32x32x16_bf16 v[112:127], v[188:191], v[136:139], v[112:127]
	ds_read_b64_tr_b16 v[196:197], v14 offset:26624
	ds_read_b64_tr_b16 v[198:199], v14 offset:27136
	v_add_f32_e32 v2, v66, v2
	v_add_f32_e32 v2, v67, v2
	v_add_f32_e32 v2, v68, v2
	v_add_f32_e32 v6, v69, v2
	v_cvt_pk_bf16_f32 v148, v64, v65
	v_cvt_pk_bf16_f32 v149, v66, v67
	s_waitcnt lgkmcnt(13)
	v_mfma_f32_32x32x16_bf16 v[96:111], v[184:187], v[132:135], v[96:111]
	ds_read_b64_tr_b16 v[2:3], v14 offset:30720
	ds_read_b64_tr_b16 v[4:5], v14 offset:31232
	v_add_f32_e32 v6, v70, v6
	v_add_f32_e32 v6, v71, v6
	v_add_f32_e32 v6, v72, v6
	v_add_f32_e32 v15, v73, v6
	v_cvt_pk_bf16_f32 v150, v68, v69
	v_cvt_pk_bf16_f32 v151, v70, v71
	s_waitcnt lgkmcnt(14)
	v_mfma_f32_32x32x16_bf16 v[112:127], v[180:183], v[132:135], v[112:127]
	ds_read_b64_tr_b16 v[6:7], v14 offset:27648
	ds_read_b64_tr_b16 v[8:9], v14 offset:28160
	v_add_f32_e32 v15, v74, v15
	v_add_f32_e32 v15, v75, v15
	v_add_f32_e32 v15, v76, v15
	v_add_f32_e32 v15, v77, v15
	v_cvt_pk_bf16_f32 v144, v72, v73
	v_cvt_pk_bf16_f32 v145, v74, v75
	s_waitcnt lgkmcnt(14)
	v_mfma_f32_32x32x16_bf16 v[96:111], v[176:179], v[128:131], v[96:111]
	ds_read_b64_tr_b16 v[192:193], v14 offset:31744
	ds_read_b64_tr_b16 v[194:195], v14 offset:32256
	v_add_f32_e32 v14, v78, v15
	v_add_f32_e32 v14, v79, v14
	v_add_f32_e32 v80, 0, v14
	v_cvt_pk_bf16_f32 v146, v76, v77
	v_cvt_pk_bf16_f32 v147, v78, v79
	v_mfma_f32_32x32x16_bf16 v[112:127], v[172:175], v[128:131], v[112:127]
	s_add_i32 s18, s7, s38
	s_mov_b32 s19, m0
	s_mov_b32 m0, s18
	s_nop 0
	global_load_lds_dwordx4 v[202:203], off
	s_mov_b32 m0, s19
	s_add_i32 s18, s60, s59
	s_mov_b32 s19, m0
	s_mov_b32 m0, s18
	s_nop 0
	global_load_lds_dwordx4 v[200:201], off
	s_mov_b32 m0, s19
	ds_read_b128 v[64:67], v204 offset:256
	ds_read_b128 v[68:71], v204 offset:288
	ds_read_b128 v[72:75], v204 offset:384
	v_add_f32_e32 v230, v0, v80
	s_waitcnt lgkmcnt(2)
	v_add_f32_e32 v82, v98, v66
	v_add_f32_e32 v83, v99, v67
	s_waitcnt lgkmcnt(1)
	v_add_f32_e32 v84, v100, v68
	v_add_f32_e32 v85, v101, v69
	s_waitcnt lgkmcnt(0)
	s_nop 0
	v_add_f32_e32 v14, v112, v72
	v_add_f32_e32 v15, v113, v73
	v_add_f32_e32 v66, v114, v74
	v_add_f32_e32 v67, v115, v75
	ds_read_b128 v[72:75], v204 offset:416
	v_add_f32_e32 v86, v102, v70
	v_add_f32_e32 v87, v103, v71
	v_add_f32_e32 v64, v96, v64
	v_add_f32_e32 v65, v97, v65
	s_waitcnt lgkmcnt(0)
	v_add_f32_e32 v68, v116, v72
	v_add_f32_e32 v69, v117, v73
	v_add_f32_e32 v70, v118, v74
	v_add_f32_e32 v71, v119, v75
	ds_read_b128 v[72:75], v204 offset:320
	ds_read_b128 v[76:79], v204 offset:448
	v_max_f32_e32 v81, v64, v65
	v_max3_f32 v81, v81, v14, v66
	v_max3_f32 v81, v81, v67, v84
	s_waitcnt lgkmcnt(1)
	v_add_f32_e32 v88, v104, v72
	v_add_f32_e32 v89, v105, v73
	s_waitcnt lgkmcnt(0)
	v_add_f32_e32 v72, v120, v76
	v_add_f32_e32 v73, v121, v77
	v_add_f32_e32 v90, v106, v74
	v_add_f32_e32 v91, v107, v75
	v_add_f32_e32 v74, v122, v78
	v_add_f32_e32 v75, v123, v79
	ds_read_b128 v[76:79], v204 offset:352
	ds_read_b128 v[94:97], v204 offset:480
	v_max3_f32 v81, v81, v85, v68
	v_max3_f32 v81, v81, v69, v88
	v_max3_f32 v81, v81, v89, v72
	s_waitcnt lgkmcnt(1)
	v_add_f32_e32 v92, v108, v76
	v_add_f32_e32 v93, v109, v77
	s_waitcnt lgkmcnt(0)
	v_add_f32_e32 v76, v124, v94
	v_add_f32_e32 v77, v125, v95
	v_add_f32_e32 v94, v110, v78
	v_add_f32_e32 v95, v111, v79
	v_add_f32_e32 v78, v126, v96
	v_add_f32_e32 v79, v127, v97
	v_max3_f32 v96, v82, v83, v15
	v_max3_f32 v96, v96, v86, v87
	v_max3_f32 v96, v96, v70, v71
	v_max3_f32 v96, v96, v90, v91
	v_max3_f32 v96, v96, v74, v75
	v_max3_f32 v81, v81, v73, v92
	v_max3_f32 v96, v96, v94, v95
	v_max3_f32 v81, v81, v93, v76
	v_max3_f32 v96, v96, v78, v79
	v_max3_f32 v0, v81, v77, v96
	v_mov_b32_e32 v80, v0
	s_nop 1
	v_permlane32_swap_b32_e32 v0, v80
	v_max_f32_e32 v80, v80, v80
	v_max_f32_e32 v0, v0, v0
	v_max_f32_e32 v0, v0, v80
	v_cmp_lt_f32_e32 vcc, s96, v0
	s_cmp_lg_u64 vcc, 0
	s_cselect_b64 s[18:19], -1, 0
	s_cbranch_vccnz .LBB0_262
